# ROW_P1: every workgroup sums the split-K partials of one sample row and its wave 0 processes it (was 64 workgroups x 4 rows serially)
# speedup vs baseline: 1.0061x; 1.0017x over previous
; __device__ __forceinline__ unsigned char* WSP() { return (unsigned char*)IN(41); }
; __device__ __forceinline__ unsigned pk2(float lo, float hi) { f32x2c v = {lo, hi}; return __builtin_bit_cast(unsigned, __builtin_convertvector(v, bf16x2c)); }
; __device__ __forceinline__ void presum_sample_rows(bf16_t* MIX, int bid, int tid) {
;     if (bid < MS / 4) {
; #pragma unroll 1
;         for (int r = 0; r < 4; ++r) {
;             const size_t off = (size_t)(4 * bid + r) * D + 4 * tid;
;             const float* pb = (const float*)(WSP() + WS_PB) + off;
;             f32x4 v[KSPLIT];
; #pragma unroll
;             for (int k = 0; k < KSPLIT; ++k) v[k] = *(const f32x4*)(pb + (size_t)k * 256 * D);
; #pragma unroll
;             for (int k = 1; k < KSPLIT; ++k) v[0] += v[k];
;             { u32x2 w; w.x = pk2(v[0][0], v[0][1]); w.y = pk2(v[0][2], v[0][3]); *(u32x2*)(MIX + (size_t)MP * D + off) = w; }
;         }
;     }
;     __syncthreads();
; }
.LBB0_978:
	s_andn2_b64 vcc, exec, s[2:3]
	s_cbranch_vccnz .LBB0_1238
	s_cmp_lt_i32 s37, 8
	s_mov_b64 s[2:3], -1
	s_cbranch_scc1 .LBB0_1011
	s_cmp_gt_i32 s37, 8
	s_cbranch_scc0 .LBB0_998
	v_mov_b32_e32 v0, v146
	s_mov_b32 s14, s67
	s_load_dwordx2 s[2:3], s[0:1], 0x150
	s_movk_i32 s8, 0x48
	v_readfirstlane_b32 s4, v0
	v_lshlrev_b32_e32 v0, 2, v0
	s_waitcnt lgkmcnt(0)
	s_mov_b32 s5, s2
	s_movk_i32 s2, 0x148
	s_ashr_i32 s3, s2, 31
	s_add_u32 s2, s0, s2
	s_addc_u32 s3, s1, s3
	s_load_dwordx2 s[6:7], s[2:3], 0x0
	s_mov_b32 s2, 64
	s_ashr_i32 s3, s2, 31
	s_add_u32 s2, s0, s2
	s_addc_u32 s3, s1, s3
	s_load_dwordx2 s[2:3], s[2:3], 0x0
	s_ashr_i32 s9, s8, 31
	s_add_u32 s8, s0, s8
	s_addc_u32 s9, s1, s9
	s_load_dwordx2 s[10:11], s[8:9], 0x0
	s_cmp_lt_i32 s14, 0x100
	s_cselect_b64 s[8:9], -1, 0
	s_cmp_gt_i32 s14, 0xff
	s_cbranch_scc1 .LBB0_984
	s_mov_b32 s12, s14
	s_ashr_i32 s13, s12, 31
	s_lshl_b64 s[16:17], s[12:13], 12
	s_waitcnt lgkmcnt(0)
	s_add_u32 s16, s6, s16
	v_ashrrev_i32_e32 v1, 31, v0
	s_addc_u32 s17, s7, s17
	s_waitcnt vmcnt(0)
	v_lshl_add_u64 v[4:5], v[0:1], 1, s[16:17]
	s_mov_b64 s[16:17], 0x12d00000
	s_lshl_b64 s[12:13], s[12:13], 13
	v_lshl_add_u64 v[4:5], v[4:5], 0, s[16:17]
	v_lshl_add_u64 v[6:7], v[0:1], 2, s[12:13]
	s_mov_b64 s[12:13], 0
.LBB0_983:
	s_movk_i32 s15, 0x148
	s_ashr_i32 s17, s15, 31
	s_add_u32 s16, s0, s15
	s_addc_u32 s17, s1, s17
	s_load_dwordx2 s[16:17], s[16:17], 0x0
	s_waitcnt lgkmcnt(0)
	v_lshl_add_u64 v[8:9], s[16:17], 0, v[6:7]
	s_waitcnt vmcnt(0)
	v_lshl_add_u64 v[68:69], v[8:9], 0, s[12:13]
	v_add_co_u32_e32 v8, vcc, 0x33e00000, v68
	s_add_u32 s12, s12, 0x2000
	s_nop 0
	v_addc_co_u32_e32 v9, vcc, 0, v69, vcc
	v_add_co_u32_e32 v12, vcc, 0x34000000, v68
	s_addc_u32 s13, s13, 0
	s_nop 0
	v_addc_co_u32_e32 v13, vcc, 0, v69, vcc
	v_add_co_u32_e32 v16, vcc, 0x34200000, v68
	global_load_dwordx4 v[8:11], v[8:9], off
	s_nop 0
	global_load_dwordx4 v[12:15], v[12:13], off
	v_addc_co_u32_e32 v17, vcc, 0, v69, vcc
	v_add_co_u32_e32 v20, vcc, 0x34400000, v68
	s_cmpk_lg_u32 s12, 0x2000
	s_nop 0
	v_addc_co_u32_e32 v21, vcc, 0, v69, vcc
	v_add_co_u32_e32 v24, vcc, 0x34600000, v68
	global_load_dwordx4 v[16:19], v[16:17], off
	s_nop 0
	global_load_dwordx4 v[20:23], v[20:21], off
	v_addc_co_u32_e32 v25, vcc, 0, v69, vcc
	v_add_co_u32_e32 v28, vcc, 0x34800000, v68
	s_waitcnt vmcnt(2)
	v_pk_add_f32 v[10:11], v[10:11], v[14:15]
	v_addc_co_u32_e32 v29, vcc, 0, v69, vcc
	v_add_co_u32_e32 v32, vcc, 0x34a00000, v68
	global_load_dwordx4 v[24:27], v[24:25], off
	s_nop 0
	global_load_dwordx4 v[28:31], v[28:29], off
	v_addc_co_u32_e32 v33, vcc, 0, v69, vcc
	v_add_co_u32_e32 v36, vcc, 0x34c00000, v68
	v_pk_add_f32 v[8:9], v[8:9], v[12:13]
	s_nop 0
	v_addc_co_u32_e32 v37, vcc, 0, v69, vcc
	v_add_co_u32_e32 v40, vcc, 0x34e00000, v68
	global_load_dwordx4 v[32:35], v[32:33], off
	s_nop 0
	global_load_dwordx4 v[36:39], v[36:37], off
	v_addc_co_u32_e32 v41, vcc, 0, v69, vcc
	v_add_co_u32_e32 v44, vcc, 0x35000000, v68
	s_waitcnt vmcnt(5)
	v_pk_add_f32 v[10:11], v[18:19], v[10:11]
	v_addc_co_u32_e32 v45, vcc, 0, v69, vcc
	v_add_co_u32_e32 v48, vcc, 0x35200000, v68
	global_load_dwordx4 v[40:43], v[40:41], off
	s_nop 0
	global_load_dwordx4 v[44:47], v[44:45], off
	v_addc_co_u32_e32 v49, vcc, 0, v69, vcc
	v_add_co_u32_e32 v52, vcc, 0x35400000, v68
	v_pk_add_f32 v[8:9], v[16:17], v[8:9]
	s_nop 0
	v_addc_co_u32_e32 v53, vcc, 0, v69, vcc
	v_add_co_u32_e32 v56, vcc, 0x35600000, v68
	global_load_dwordx4 v[48:51], v[48:49], off
	s_nop 0
	global_load_dwordx4 v[52:55], v[52:53], off
	v_addc_co_u32_e32 v57, vcc, 0, v69, vcc
	v_add_co_u32_e32 v60, vcc, 0x35800000, v68
	s_waitcnt vmcnt(8)
	v_pk_add_f32 v[10:11], v[22:23], v[10:11]
	v_addc_co_u32_e32 v61, vcc, 0, v69, vcc
	v_add_co_u32_e32 v64, vcc, 0x35a00000, v68
	global_load_dwordx4 v[56:59], v[56:57], off
	s_nop 0
	global_load_dwordx4 v[60:63], v[60:61], off
	v_addc_co_u32_e32 v65, vcc, 0, v69, vcc
	v_add_co_u32_e32 v68, vcc, 0x35c00000, v68
	global_load_dwordx4 v[64:67], v[64:65], off
	s_nop 0
	v_addc_co_u32_e32 v69, vcc, 0, v69, vcc
	global_load_dwordx4 v[68:71], v[68:69], off
	v_pk_add_f32 v[8:9], v[20:21], v[8:9]
	s_waitcnt vmcnt(11)
	v_pk_add_f32 v[10:11], v[26:27], v[10:11]
	v_pk_add_f32 v[8:9], v[24:25], v[8:9]
	s_waitcnt vmcnt(10)
	v_pk_add_f32 v[10:11], v[30:31], v[10:11]
	v_pk_add_f32 v[8:9], v[28:29], v[8:9]
	s_waitcnt vmcnt(9)
	v_pk_add_f32 v[10:11], v[34:35], v[10:11]
	v_pk_add_f32 v[8:9], v[32:33], v[8:9]
	s_waitcnt vmcnt(8)
	v_pk_add_f32 v[10:11], v[38:39], v[10:11]
	v_pk_add_f32 v[8:9], v[36:37], v[8:9]
	s_waitcnt vmcnt(7)
	v_pk_add_f32 v[10:11], v[42:43], v[10:11]
	v_pk_add_f32 v[8:9], v[40:41], v[8:9]
	s_waitcnt vmcnt(6)
	v_pk_add_f32 v[10:11], v[46:47], v[10:11]
	v_pk_add_f32 v[8:9], v[44:45], v[8:9]
	s_waitcnt vmcnt(5)
	v_pk_add_f32 v[10:11], v[50:51], v[10:11]
	v_pk_add_f32 v[8:9], v[48:49], v[8:9]
	s_waitcnt vmcnt(4)
	v_pk_add_f32 v[10:11], v[54:55], v[10:11]
	v_pk_add_f32 v[8:9], v[52:53], v[8:9]
	s_waitcnt vmcnt(3)
	v_pk_add_f32 v[10:11], v[58:59], v[10:11]
	v_pk_add_f32 v[8:9], v[56:57], v[8:9]
	s_waitcnt vmcnt(2)
	v_pk_add_f32 v[10:11], v[62:63], v[10:11]
	v_pk_add_f32 v[8:9], v[60:61], v[8:9]
	s_waitcnt vmcnt(1)
	v_pk_add_f32 v[10:11], v[66:67], v[10:11]
	v_pk_add_f32 v[8:9], v[64:65], v[8:9]
	s_waitcnt vmcnt(0)
	v_pk_add_f32 v[10:11], v[70:71], v[10:11]
	v_pk_add_f32 v[8:9], v[68:69], v[8:9]
	s_nop 0
	v_cvt_pk_bf16_f32 v8, v8, v9
	v_cvt_pk_bf16_f32 v9, v10, v11
	global_store_dwordx2 v[4:5], v[8:9], off
	v_lshl_add_u64 v[4:5], v[4:5], 0, s[56:57]
	s_cbranch_scc1 .LBB0_983
; __device__ __forceinline__ unsigned char* WSP() { return (unsigned char*)IN(41); }
; __device__ __forceinline__ int TID() { int t = threadIdx.x; asm volatile("" : "+v"(t)); return t; }
; __device__ __forceinline__ int BID() { int b = blockIdx.x; asm volatile("" : "+s"(b)); return b; }
; __device__ __forceinline__ int GSZ() { int g = gridDim.x; asm volatile("" : "+s"(g)); return g; }
; __device__ __forceinline__ unsigned pk2(float lo, float hi) { f32x2c v = {lo, hi}; return __builtin_bit_cast(unsigned, __builtin_convertvector(v, bf16x2c)); }
; __device__ __forceinline__ int rfl(int v) { return __builtin_amdgcn_readfirstlane(v); }
; __device__ __forceinline__ void row_post1(const Params& p, int layer) {
;     const int tid_ = TID(), lane = tid_ & 63, wave_ = rfl(tid_ >> 6), bid_ = BID(), gw = bid_ * 8 + wave_, ngw = GSZ() * 8;
;     unsigned char* ws = WSP();
;     bf16_t* X = (bf16_t*)(ws + ((layer & 1) ? WS_XB : WS_XA));
;     const bf16_t* MIX = (const bf16_t*)(ws + WS_MIX);
;     const float* g1 = IN(8) + (size_t)layer * D; const float* g2 = IN(9) + (size_t)layer * D;
;     presum_sample_rows((bf16_t*)(ws + WS_MIX), bid_, tid_);
;     const int nit = (MP - gw + ngw - 1) / ngw;
;     for (int it_ = 0; it_ <= nit; ++it_) {
;         int m = gw + it_ * ngw;
;         if (it_ == nit) { if (wave_ >= 4 || bid_ >= MS / 4) break; m = MP + 4 * bid_ + wave_; }
;         f32x4 x[8], mx[8];
;         xrow_load(X, layer == 0, m, lane, x);
;         row_load_bf16(MIX + (size_t)m * D, lane, mx);
;         const float rs = row_rstd(mx);
; #pragma unroll
;         for (int j = 0; j < 8; ++j) { const f32x4 g = *(const f32x4*)(g1 + 256 * j + 4 * lane); x[j] += mx[j] * rs * g; u32x2 w; w.x = pk2(x[j][0], x[j][1]); w.y = pk2(x[j][2], x[j][3]); *(u32x2*)(X + (size_t)m * D + 256 * j + 4 * lane) = w; }
;         const float rs2 = row_rstd(x);
; #pragma unroll
;         for (int j = 0; j < 8; ++j) { const f32x4 g = *(const f32x4*)(g2 + 256 * j + 4 * lane); x[j] = x[j] * rs2 * g; }
.LBB0_984:
	s_lshl_b32 s5, s5, 3
	s_abs_i32 s15, s5
	v_cvt_f32_u32_e32 v1, s15
	s_ashr_i32 s12, s4, 6
	s_lshl_b32 s4, s14, 3
	s_add_i32 s4, s4, s12
	v_rcp_iflag_f32_e32 v1, v1
	s_sub_i32 s16, s5, s4
	s_add_i32 s17, s16, 0x1fff
	s_sub_i32 s16, 0xffffe001, s16
	v_mul_f32_e32 v1, 0x4f7ffffe, v1
	v_cvt_u32_f32_e32 v1, v1
	s_xor_b32 s13, s17, s5
	s_max_i32 s16, s17, s16
	s_sub_i32 s17, 0, s15
	v_readfirstlane_b32 s18, v1
	s_mul_i32 s17, s17, s18
	s_mul_hi_u32 s17, s18, s17
	s_add_i32 s18, s18, s17
	s_mul_hi_u32 s17, s16, s18
	s_mul_i32 s18, s17, s15
	s_sub_i32 s16, s16, s18
	s_ashr_i32 s13, s13, 31
	s_add_i32 s18, s17, 1
	s_sub_i32 s19, s16, s15
	s_cmp_ge_u32 s16, s15
	s_cselect_b32 s17, s18, s17
	s_cselect_b32 s16, s19, s16
	s_add_i32 s18, s17, 1
	s_cmp_ge_u32 s16, s15
	s_cselect_b32 s15, s18, s17
	s_xor_b32 s15, s15, s13
	s_sub_i32 s16, s15, s13
	s_cmp_lt_i32 s16, 0
	s_waitcnt lgkmcnt(0)
	s_barrier
	s_cbranch_scc1 .LBB0_997
	v_readlane_b32 s16, v234, 26
	s_add_u32 s16, s6, s16
	s_addc_u32 s17, s7, 0
	v_readlane_b32 s20, v234, 52
	v_readlane_b32 s21, v234, 53
	s_add_u32 s18, s2, s20
	s_addc_u32 s19, s3, s21
	s_add_u32 s10, s10, s20
	s_addc_u32 s11, s11, s21
	s_waitcnt vmcnt(0)
	v_and_b32_e32 v4, 0xfc, v0
	s_cmp_lt_i32 s12, 1
	v_lshlrev_b32_e32 v2, 1, v4
	s_cselect_b64 s[2:3], -1, 0
	v_lshl_add_u64 v[6:7], s[6:7], 0, v[2:3]
	s_mov_b64 s[6:7], 0x10d00000
	s_and_b64 s[2:3], s[2:3], s[8:9]
	s_mov_b32 s8, s14
	v_lshl_add_u64 v[0:1], s[16:17], 0, v[2:3]
	s_waitcnt vmcnt(0)
	v_lshl_add_u64 v[40:41], v[6:7], 0, s[6:7]
	v_lshlrev_b32_e32 v2, 2, v4
	s_mov_b64 s[6:7], 0xec00000
	s_add_i32 s12, s12, s8
	v_lshl_add_u64 v[42:43], s[18:19], 0, v[2:3]
	v_lshl_add_u64 v[44:45], s[10:11], 0, v[2:3]
	v_lshl_add_u64 v[46:47], v[6:7], 0, s[6:7]
	s_mov_b64 s[6:7], 0x1400
	s_mov_b64 s[8:9], 0x1800
	s_mov_b64 s[10:11], 0x1c00
	s_addk_i32 s12, 0x2000
	v_lshl_add_u64 v[48:49], v[42:43], 0, s[56:57]
	v_lshl_add_u64 v[50:51], v[42:43], 0, s[6:7]
	v_lshl_add_u64 v[52:53], v[42:43], 0, s[8:9]
	v_lshl_add_u64 v[54:55], v[42:43], 0, s[10:11]
	v_lshl_add_u64 v[56:57], v[44:45], 0, s[56:57]
	v_lshl_add_u64 v[58:59], v[44:45], 0, s[6:7]
	v_lshl_add_u64 v[60:61], v[44:45], 0, s[8:9]
	v_lshl_add_u64 v[62:63], v[44:45], 0, s[10:11]
	s_sub_i32 s13, s13, s15
	v_lshlrev_b32_e32 v2, 2, v4
	global_load_dwordx4 v[160:163], v[42:43], off
	global_load_dwordx4 v[164:167], v[42:43], off offset:1024
	global_load_dwordx4 v[168:171], v[42:43], off offset:2048
	global_load_dwordx4 v[172:175], v[42:43], off offset:3072
	global_load_dwordx4 v[176:179], v[48:49], off
	global_load_dwordx4 v[180:183], v[50:51], off
	global_load_dwordx4 v[184:187], v[52:53], off
	global_load_dwordx4 v[188:191], v[54:55], off
	global_load_dwordx4 v[192:195], v[44:45], off
	global_load_dwordx4 v[196:199], v[44:45], off offset:1024
	global_load_dwordx4 v[200:203], v[44:45], off offset:2048
	global_load_dwordx4 v[204:207], v[44:45], off offset:3072
	global_load_dwordx4 v[208:211], v[56:57], off
	global_load_dwordx4 v[212:215], v[58:59], off
	global_load_dwordx4 v[216:219], v[60:61], off
	global_load_dwordx4 v[220:223], v[62:63], off
	s_branch .LBB0_989
